# v23 = v22 + PV phase exps rotated two MFMA gaps later (MFMA-only head after the per-step barrier)
# baseline (speedup 1.0000x reference)
.Lstg_mid1:
	ds_read_b64_tr_b16 v[40:41], v167 offset:54272
	ds_read_b64_tr_b16 v[42:43], v167 offset:54784
	s_waitcnt lgkmcnt(6)
	v_mfma_f32_32x32x16_bf16 v[16:31], v[132:135], v[32:35], v[16:31]
	ds_read_b64_tr_b16 v[32:33], v167 offset:51200
	ds_read_b64_tr_b16 v[34:35], v167 offset:51712
	s_waitcnt lgkmcnt(6)
	v_mfma_f32_32x32x16_bf16 v[0:15], v[132:135], v[48:51], v[0:15]
	ds_read_b64_tr_b16 v[44:45], v167 offset:55296
	ds_read_b64_tr_b16 v[46:47], v167 offset:55808
	s_waitcnt lgkmcnt(6)
	v_mfma_f32_32x32x16_bf16 v[16:31], v[128:131], v[36:39], v[16:31]
	v_exp_f32_e32 v80, v80
	v_exp_f32_e32 v81, v81
	v_exp_f32_e32 v82, v82
	v_exp_f32_e32 v83, v83
	ds_read_b64_tr_b16 v[48:49], v167 offset:52224
	ds_read_b64_tr_b16 v[50:51], v167 offset:52736
	s_waitcnt lgkmcnt(6)
	v_mfma_f32_32x32x16_bf16 v[0:15], v[128:131], v[40:43], v[0:15]
	v_exp_f32_e32 v84, v84
	v_exp_f32_e32 v85, v85
	v_exp_f32_e32 v86, v86
	v_exp_f32_e32 v87, v87
	ds_read_b64_tr_b16 v[40:41], v167 offset:56320
	ds_read_b64_tr_b16 v[42:43], v167 offset:56832
	s_waitcnt lgkmcnt(6)
	v_mfma_f32_32x32x16_bf16 v[16:31], v[124:127], v[32:35], v[16:31]
	v_exp_f32_e32 v88, v88
	v_exp_f32_e32 v89, v89
	v_exp_f32_e32 v90, v90
	v_exp_f32_e32 v91, v91
	v_add_u32_e32 v142, s83, v179
	ds_read_b128 v[32:35], v142
	s_waitcnt lgkmcnt(5)
	v_mfma_f32_32x32x16_bf16 v[0:15], v[124:127], v[44:47], v[0:15]
	v_exp_f32_e32 v92, v92
	v_exp_f32_e32 v93, v93
	v_exp_f32_e32 v94, v94
	v_exp_f32_e32 v95, v95
	ds_read_b128 v[36:39], v142 offset:512
	s_waitcnt lgkmcnt(4)
	v_mfma_f32_32x32x16_bf16 v[16:31], v[120:123], v[48:51], v[16:31]
	v_exp_f32_e32 v64, v64
	v_exp_f32_e32 v65, v65
	v_exp_f32_e32 v66, v66
	v_exp_f32_e32 v67, v67
	ds_read_b128 v[136:139], v142 offset:2048
	s_waitcnt lgkmcnt(3)
	v_mfma_f32_32x32x16_bf16 v[0:15], v[120:123], v[40:43], v[0:15]
	v_exp_f32_e32 v68, v68
	v_exp_f32_e32 v69, v69
	v_exp_f32_e32 v70, v70
	v_exp_f32_e32 v71, v71
	v_exp_f32_e32 v72, v72
	v_exp_f32_e32 v73, v73
	v_exp_f32_e32 v74, v74
	v_exp_f32_e32 v75, v75
	v_exp_f32_e32 v76, v76
	v_exp_f32_e32 v77, v77
	v_exp_f32_e32 v78, v78
	v_exp_f32_e32 v79, v79
	s_cmp_lt_u32 s90, 4
	s_cbranch_scc0 .Lstg_end1
	s_waitcnt vmcnt(3) lgkmcnt(0)
	s_barrier

.Lstg_mid2:
	s_add_i32 s0, s83, 0x3000
	s_cmpk_lg_u32 s83, 0x9000
	s_cselect_b32 s82, s0, 0
	ds_read_b64_tr_b16 v[72:73], v141 offset:54272
	ds_read_b64_tr_b16 v[74:75], v141 offset:54784
	s_waitcnt lgkmcnt(6)
	v_mfma_f32_32x32x16_bf16 v[16:31], v[132:135], v[64:67], v[16:31]
	ds_read_b64_tr_b16 v[64:65], v141 offset:51200
	ds_read_b64_tr_b16 v[66:67], v141 offset:51712
	s_waitcnt lgkmcnt(6)
	v_mfma_f32_32x32x16_bf16 v[0:15], v[132:135], v[80:83], v[0:15]
	s_add_i32 s0, s79, 0x2000
	s_cmpk_lg_i32 s79, 0x4000
	s_cselect_b32 s0, s0, 0xe800
	s_cmpk_lg_u32 s79, 0xe800
	s_cselect_b32 s84, s0, 0
	ds_read_b64_tr_b16 v[76:77], v141 offset:55296
	ds_read_b64_tr_b16 v[78:79], v141 offset:55808
	s_waitcnt lgkmcnt(6)
	v_mfma_f32_32x32x16_bf16 v[16:31], v[128:131], v[68:71], v[16:31]
	v_exp_f32_e32 v48, v48
	v_exp_f32_e32 v49, v49
	v_exp_f32_e32 v50, v50
	v_exp_f32_e32 v51, v51
	s_add_i32 s0, s82, 0x3000
	s_cmpk_lg_u32 s82, 0x9000
	s_cselect_b32 s85, s0, 0
	ds_read_b64_tr_b16 v[68:69], v141 offset:52224
	ds_read_b64_tr_b16 v[70:71], v141 offset:52736
	s_waitcnt lgkmcnt(6)
	v_mfma_f32_32x32x16_bf16 v[0:15], v[128:131], v[72:75], v[0:15]
	v_exp_f32_e32 v52, v52
	v_exp_f32_e32 v53, v53
	v_exp_f32_e32 v54, v54
	v_exp_f32_e32 v55, v55
	s_add_u32 s68, s68, 0x30000
	s_addc_u32 s69, s69, 0
	ds_read_b64_tr_b16 v[72:73], v141 offset:56320
	ds_read_b64_tr_b16 v[74:75], v141 offset:56832
	s_waitcnt lgkmcnt(6)
	v_mfma_f32_32x32x16_bf16 v[16:31], v[124:127], v[64:67], v[16:31]
	v_exp_f32_e32 v56, v56
	v_exp_f32_e32 v57, v57
	v_exp_f32_e32 v58, v58
	v_exp_f32_e32 v59, v59
	s_add_u32 s48, s48, 0x48000
	s_addc_u32 s49, s49, 0
	v_add_u32_e32 v64, s82, v179
	ds_read_b128 v[80:83], v64
	s_waitcnt lgkmcnt(5)
	v_mfma_f32_32x32x16_bf16 v[0:15], v[124:127], v[76:79], v[0:15]
	v_exp_f32_e32 v60, v60
	v_exp_f32_e32 v61, v61
	v_exp_f32_e32 v62, v62
	v_exp_f32_e32 v63, v63
	s_add_u32 s8, s8, 0x2000
	s_addc_u32 s9, s9, 0
	ds_read_b128 v[136:139], v64 offset:512
	s_waitcnt lgkmcnt(4)
	v_mfma_f32_32x32x16_bf16 v[16:31], v[120:123], v[68:71], v[16:31]
	v_exp_f32_e32 v32, v32
	v_exp_f32_e32 v33, v33
	v_exp_f32_e32 v34, v34
	v_exp_f32_e32 v35, v35
	s_add_i32 s0, s87, 2
	ds_read_b128 v[140:143], v64 offset:2048
	s_waitcnt lgkmcnt(3)
	v_mfma_f32_32x32x16_bf16 v[0:15], v[120:123], v[72:75], v[0:15]
	v_exp_f32_e32 v36, v36
	v_exp_f32_e32 v37, v37
	v_exp_f32_e32 v38, v38
	v_exp_f32_e32 v39, v39
	v_exp_f32_e32 v40, v40
	v_exp_f32_e32 v41, v41
	v_exp_f32_e32 v42, v42
	v_exp_f32_e32 v43, v43
	v_exp_f32_e32 v44, v44
	v_exp_f32_e32 v45, v45
	v_exp_f32_e32 v46, v46
	v_exp_f32_e32 v47, v47
	s_cmp_lt_u32 s90, 4
	s_cbranch_scc0 .Lstg_end2
	s_waitcnt vmcnt(3) lgkmcnt(0)
	s_barrier
